# DSA selection: dead K-fragment register copies only on the no-prefetch path; ballot masks taken from the compare masks directly
# speedup vs baseline: 1.0770x; 1.0116x over previous
;   __device__ __forceinline__ u16* KIDX() const { return (u16*)(ws + O_KIDX); }
; DI f32x16 mfma32(bf16x8 a, bf16x8 b, f32x16 c) { return __builtin_amdgcn_mfma_f32_32x32x16_bf16(a, b, c, 0, 0, 0); }
; DI u32 mono_key(float f) { u32 u = __float_as_uint(f); return (u & 0x80000000u) ? ~u : (u | 0x80000000u); }
; DI void dsa_item(const Params& p, int l, int tile32, int b, char* smem) {
;     ...
;       bf16x8 kc[4][4];
; #pragma unroll
;       for (int t = 0; t < 4; ++t)
; #pragma unroll
;         for (int s = 0; s < 4; ++s) kc[t][s] = kn[t][s];
;       if (g + 1 < ngrp) {
; #pragma unroll
;         for (int t = 0; t < 4; ++t) {
;           const u16* krow = p.KIDX() + (tokbase + (g + 1) * 128 + t * 32 + c31) * 64 + 8 * hh;
; #pragma unroll
;           for (int s = 0; s < 4; ++s) kn[t][s] = *(const bf16x8*)(krow + 16 * s);
;         }
;       }
;       const u32 tauA = hh ? tau2 : tau0, tauB = hh ? tau3 : tau1;
; #pragma unroll
;       for (int t = 0; t < 4; ++t) {
;         const int key = (g * 4 + t) * 32 + c31;
;         f32x16 acc;
; #pragma unroll
;         for (int j = 0; j < 16; ++j) acc[j] = 0.f;
; #pragma unroll
;         for (int s = 0; s < 4; ++s) acc = mfma32(qa[s], kc[t][s], acc);
;         f32x2 ss2 = f32x2{0.f, 0.f};
; #pragma unroll
;         for (int hq = 0; hq < 8; ++hq) {
;           const f32x2 rr = f32x2{__builtin_amdgcn_fmed3f(acc[2 * hq], 0.f, 3.0e38f), __builtin_amdgcn_fmed3f(acc[2 * hq + 1], 0.f, 3.0e38f)};
;           ss2 = __builtin_elementwise_fma(wq2[hq], rr, ss2);
;         }
;         const float s0 = ss2.x, s1 = ss2.y;
;         const u32 k0 = mono_key(s0), k1 = mono_key(s1);
;         const bool c0 = (key <= qpos0) && (k0 > tauA), c1 = (key <= qpos0 + 1) && (k1 > tauB);
;         const u64 m0 = __ballot(c0), m1 = __ballot(c1);
;         if (m0 | m1) {
;           const u32 h0 = hh ? (u32)(m0 >> 32) : (u32)m0, h1 = hh ? (u32)(m1 >> 32) : (u32)m1;
;           const int pA = (hh ? cnt2 : cnt0) + __popc(h0 & lmask), pB = (hh ? cnt3 : cnt1) + __popc(h1 & lmask);
;           if (c0) { ckey[(2 * hh) * DCAP + pA] = k0; cidx[(2 * hh) * DCAP + pA] = (u16)key; }
;           if (c1) { ckey[(2 * hh + 1) * DCAP + pB] = k1; cidx[(2 * hh + 1) * DCAP + pB] = (u16)key; }
;           cnt0 += __popc((u32)m0); cnt2 += __popc((u32)(m0 >> 32));
;           cnt1 += __popc((u32)m1); cnt3 += __popc((u32)(m1 >> 32));
;         }
.LBB0_496:
	s_or_b64 exec, exec, s[96:97]
	s_add_i32 s12, s54, 1
	s_and_saveexec_b64 s[8:9], s[0:1]
	s_cbranch_execz .LBB0_375
	s_waitcnt vmcnt(2)
	s_waitcnt lgkmcnt(0)
	s_waitcnt vmcnt(0)
	v_cmp_lt_i32_e64 s[0:1], s12, v210
	s_and_saveexec_b64 s[2:3], s[0:1]
	s_cbranch_execz .Ldsa_keep
	v_lshl_add_u32 v0, s12, 7, v211
	v_lshlrev_b64 v[6:7], 7, v[0:1]
	v_lshl_add_u64 v[6:7], v[176:177], 0, v[6:7]
	global_load_dwordx4 v[102:105], v[6:7], off
	global_load_dwordx4 v[106:109], v[6:7], off offset:1024
	global_load_dwordx4 v[110:113], v[6:7], off offset:2048
	global_load_dwordx4 v[114:117], v[6:7], off offset:3072
	v_or_b32_e32 v6, 32, v0
	v_mov_b32_e32 v7, v1
	v_lshlrev_b64 v[6:7], 7, v[6:7]
	v_lshl_add_u64 v[6:7], v[176:177], 0, v[6:7]
	global_load_dwordx4 v[118:121], v[6:7], off
	global_load_dwordx4 v[122:125], v[6:7], off offset:1024
	global_load_dwordx4 v[126:129], v[6:7], off offset:2048
	global_load_dwordx4 v[130:133], v[6:7], off offset:3072
	v_or_b32_e32 v6, 64, v0
	v_mov_b32_e32 v7, v1
	v_lshlrev_b64 v[6:7], 7, v[6:7]
	v_lshl_add_u64 v[6:7], v[176:177], 0, v[6:7]
	v_or_b32_e32 v0, 0x60, v0
	global_load_dwordx4 v[134:137], v[6:7], off
	global_load_dwordx4 v[138:141], v[6:7], off offset:1024
	global_load_dwordx4 v[142:145], v[6:7], off offset:2048
	global_load_dwordx4 v[146:149], v[6:7], off offset:3072
	v_lshlrev_b64 v[6:7], 7, v[0:1]
	v_lshl_add_u64 v[6:7], v[176:177], 0, v[6:7]
	global_load_dwordx4 v[150:153], v[6:7], off
	global_load_dwordx4 v[154:157], v[6:7], off offset:1024
	global_load_dwordx4 v[158:161], v[6:7], off offset:2048
	global_load_dwordx4 v[162:165], v[6:7], off offset:3072
	s_branch .LBB0_499
.Ldsa_keep:
	s_or_b64 exec, exec, s[2:3]
	v_mov_b64_e32 v[104:105], v[4:5]
	v_mov_b64_e32 v[108:109], v[100:101]
	v_mov_b64_e32 v[112:113], v[96:97]
	v_mov_b64_e32 v[116:117], v[92:93]
	v_mov_b64_e32 v[120:121], v[88:89]
	v_mov_b64_e32 v[124:125], v[84:85]
	v_mov_b64_e32 v[128:129], v[80:81]
	v_mov_b64_e32 v[132:133], v[76:77]
	v_mov_b64_e32 v[136:137], v[72:73]
	v_mov_b64_e32 v[140:141], v[68:69]
	v_mov_b64_e32 v[144:145], v[64:65]
	v_mov_b64_e32 v[148:149], v[60:61]
	v_mov_b64_e32 v[152:153], v[56:57]
	v_mov_b64_e32 v[156:157], v[52:53]
	v_mov_b64_e32 v[160:161], v[48:49]
	v_mov_b64_e32 v[164:165], v[44:45]
	v_mov_b64_e32 v[102:103], v[2:3]
	v_mov_b64_e32 v[106:107], v[98:99]
	v_mov_b64_e32 v[110:111], v[94:95]
	v_mov_b64_e32 v[114:115], v[90:91]
	v_mov_b64_e32 v[118:119], v[86:87]
	v_mov_b64_e32 v[122:123], v[82:83]
	v_mov_b64_e32 v[126:127], v[78:79]
	v_mov_b64_e32 v[130:131], v[74:75]
	v_mov_b64_e32 v[134:135], v[70:71]
	v_mov_b64_e32 v[138:139], v[66:67]
	v_mov_b64_e32 v[142:143], v[62:63]
	v_mov_b64_e32 v[146:147], v[58:59]
	v_mov_b64_e32 v[150:151], v[54:55]
	v_mov_b64_e32 v[154:155], v[50:51]
	v_mov_b64_e32 v[158:159], v[46:47]
	v_mov_b64_e32 v[162:163], v[42:43]
.LBB0_499:
	s_or_b64 exec, exec, s[2:3]
	v_mfma_f32_32x32x16_bf16 v[2:17], v[18:21], v[2:5], 0
	v_cndmask_b32_e32 v0, v223, v224, vcc
	v_mfma_f32_32x32x16_bf16 v[2:17], v[22:25], v[98:101], v[2:17]
	v_mfma_f32_32x32x16_bf16 v[2:17], v[26:29], v[94:97], v[2:17]
	v_lshl_or_b32 v95, s54, 7, v192
	v_cndmask_b32_e32 v94, v221, v222, vcc
	v_cmp_le_i32_e64 s[0:1], v95, v217
	v_cmp_le_i32_e64 s[2:3], v95, v219
	v_mfma_f32_32x32x16_bf16 v[2:17], v[30:33], v[90:93], v[2:17]
	s_nop 11
	v_med3_f32 v2, v2, 0, v204
	v_med3_f32 v3, v3, 0, v204
	v_med3_f32 v4, v4, 0, v204
	v_med3_f32 v5, v5, 0, v204
	v_pk_fma_f32 v[2:3], v[178:179], v[2:3], 0 op_sel_hi:[1,1,0]
	v_med3_f32 v6, v6, 0, v204
	v_med3_f32 v7, v7, 0, v204
	v_pk_fma_f32 v[2:3], v[38:39], v[4:5], v[2:3]
	v_med3_f32 v8, v8, 0, v204
	v_med3_f32 v9, v9, 0, v204
	v_pk_fma_f32 v[2:3], v[180:181], v[6:7], v[2:3]
	v_med3_f32 v10, v10, 0, v204
	v_med3_f32 v11, v11, 0, v204
	v_pk_fma_f32 v[2:3], v[40:41], v[8:9], v[2:3]
	v_med3_f32 v12, v12, 0, v204
	v_med3_f32 v13, v13, 0, v204
	v_pk_fma_f32 v[2:3], v[182:183], v[10:11], v[2:3]
	v_med3_f32 v14, v14, 0, v204
	v_med3_f32 v15, v15, 0, v204
	v_pk_fma_f32 v[2:3], v[34:35], v[12:13], v[2:3]
	v_med3_f32 v16, v16, 0, v204
	v_med3_f32 v17, v17, 0, v204
	v_pk_fma_f32 v[2:3], v[184:185], v[14:15], v[2:3]
	s_nop 0
	v_pk_fma_f32 v[4:5], v[36:37], v[16:17], v[2:3]
	s_nop 0
	v_not_b32_e32 v2, v4
	v_or_b32_e32 v3, 0x80000000, v4
	v_cmp_gt_i32_e64 s[4:5], 0, v4
	v_not_b32_e32 v6, v5
	v_or_b32_e32 v7, 0x80000000, v5
	v_cndmask_b32_e64 v3, v3, v2, s[4:5]
	v_cmp_gt_i32_e64 s[4:5], 0, v5
	s_nop 1
	v_cndmask_b32_e64 v2, v7, v6, s[4:5]
	v_cmp_gt_u32_e64 s[4:5], v3, v0
	v_cmp_gt_u32_e64 s[6:7], v2, v94
	s_and_b64 s[10:11], s[0:1], s[4:5]
	s_and_b64 s[4:5], s[2:3], s[6:7]
	s_and_b64 s[0:1], s[10:11], exec
	s_and_b64 s[2:3], s[4:5], exec
	s_or_b64 s[6:7], s[2:3], s[0:1]
	s_cmp_eq_u64 s[6:7], 0
	s_cbranch_scc1 .LBB0_505
	s_and_saveexec_b64 s[6:7], s[10:11]
	s_cbranch_execz .LBB0_502
	v_mov_b32_e32 v4, s1
	v_mov_b32_e32 v5, s0
	v_cndmask_b32_e32 v4, v4, v5, vcc
	v_and_b32_e32 v4, v4, v218
	v_bcnt_u32_b32 v4, v4, 0
	v_cndmask_b32_e32 v5, v187, v173, vcc
	v_add3_u32 v4, v5, v214, v4
	v_lshl_add_u32 v5, v4, 2, v190
	ds_write_b32 v5, v3
	v_lshlrev_b32_e32 v3, 1, v4
	v_sub_u32_e32 v3, v5, v3
	ds_write_b16 v3, v95 offset:10240

; DI f32x16 mfma32(bf16x8 a, bf16x8 b, f32x16 c) { return __builtin_amdgcn_mfma_f32_32x32x16_bf16(a, b, c, 0, 0, 0); }
; DI u32 mono_key(float f) { u32 u = __float_as_uint(f); return (u & 0x80000000u) ? ~u : (u | 0x80000000u); }
; DI void dsa_item(const Params& p, int l, int tile32, int b, char* smem) {
;     ...
;       for (int t = 0; t < 4; ++t) {
;         const int key = (g * 4 + t) * 32 + c31;
;         f32x16 acc;
; #pragma unroll
;         for (int j = 0; j < 16; ++j) acc[j] = 0.f;
; #pragma unroll
;         for (int s = 0; s < 4; ++s) acc = mfma32(qa[s], kc[t][s], acc);
;         f32x2 ss2 = f32x2{0.f, 0.f};
; #pragma unroll
;         for (int hq = 0; hq < 8; ++hq) {
;           const f32x2 rr = f32x2{__builtin_amdgcn_fmed3f(acc[2 * hq], 0.f, 3.0e38f), __builtin_amdgcn_fmed3f(acc[2 * hq + 1], 0.f, 3.0e38f)};
;           ss2 = __builtin_elementwise_fma(wq2[hq], rr, ss2);
;         }
;         const float s0 = ss2.x, s1 = ss2.y;
;         const u32 k0 = mono_key(s0), k1 = mono_key(s1);
;         const bool c0 = (key <= qpos0) && (k0 > tauA), c1 = (key <= qpos0 + 1) && (k1 > tauB);
;         const u64 m0 = __ballot(c0), m1 = __ballot(c1);
;         if (m0 | m1) {
;           const u32 h0 = hh ? (u32)(m0 >> 32) : (u32)m0, h1 = hh ? (u32)(m1 >> 32) : (u32)m1;
;           const int pA = (hh ? cnt2 : cnt0) + __popc(h0 & lmask), pB = (hh ? cnt3 : cnt1) + __popc(h1 & lmask);
;           if (c0) { ckey[(2 * hh) * DCAP + pA] = k0; cidx[(2 * hh) * DCAP + pA] = (u16)key; }
;           if (c1) { ckey[(2 * hh + 1) * DCAP + pB] = k1; cidx[(2 * hh + 1) * DCAP + pB] = (u16)key; }
;           cnt0 += __popc((u32)m0); cnt2 += __popc((u32)(m0 >> 32));
;           cnt1 += __popc((u32)m1); cnt3 += __popc((u32)(m1 >> 32));
;         }
.LBB0_505:
	v_mfma_f32_32x32x16_bf16 v[2:17], v[18:21], v[86:89], 0
	v_mfma_f32_32x32x16_bf16 v[2:17], v[22:25], v[82:85], v[2:17]
	v_mfma_f32_32x32x16_bf16 v[2:17], v[26:29], v[78:81], v[2:17]
	v_or_b32_e32 v78, 32, v95
	v_cmp_le_i32_e64 s[0:1], v78, v217
	v_cmp_le_i32_e64 s[2:3], v78, v219
	v_mfma_f32_32x32x16_bf16 v[2:17], v[30:33], v[74:77], v[2:17]
	s_nop 11
	v_med3_f32 v2, v2, 0, v204
	v_med3_f32 v3, v3, 0, v204
	v_med3_f32 v4, v4, 0, v204
	v_med3_f32 v5, v5, 0, v204
	v_pk_fma_f32 v[2:3], v[178:179], v[2:3], 0 op_sel_hi:[1,1,0]
	v_med3_f32 v6, v6, 0, v204
	v_med3_f32 v7, v7, 0, v204
	v_pk_fma_f32 v[2:3], v[38:39], v[4:5], v[2:3]
	v_med3_f32 v8, v8, 0, v204
	v_med3_f32 v9, v9, 0, v204
	v_pk_fma_f32 v[2:3], v[180:181], v[6:7], v[2:3]
	v_med3_f32 v10, v10, 0, v204
	v_med3_f32 v11, v11, 0, v204
	v_pk_fma_f32 v[2:3], v[40:41], v[8:9], v[2:3]
	v_med3_f32 v12, v12, 0, v204
	v_med3_f32 v13, v13, 0, v204
	v_pk_fma_f32 v[2:3], v[182:183], v[10:11], v[2:3]
	v_med3_f32 v14, v14, 0, v204
	v_med3_f32 v15, v15, 0, v204
	v_pk_fma_f32 v[2:3], v[34:35], v[12:13], v[2:3]
	v_med3_f32 v16, v16, 0, v204
	v_med3_f32 v17, v17, 0, v204
	v_pk_fma_f32 v[2:3], v[184:185], v[14:15], v[2:3]
	s_nop 0
	v_pk_fma_f32 v[4:5], v[36:37], v[16:17], v[2:3]
	s_nop 0
	v_not_b32_e32 v2, v4
	v_or_b32_e32 v3, 0x80000000, v4
	v_cmp_gt_i32_e64 s[4:5], 0, v4
	v_not_b32_e32 v6, v5
	v_or_b32_e32 v7, 0x80000000, v5
	v_cndmask_b32_e64 v3, v3, v2, s[4:5]
	v_cmp_gt_i32_e64 s[4:5], 0, v5
	s_nop 1
	v_cndmask_b32_e64 v2, v7, v6, s[4:5]
	v_cmp_gt_u32_e64 s[4:5], v3, v0
	v_cmp_gt_u32_e64 s[6:7], v2, v94
	s_and_b64 s[10:11], s[0:1], s[4:5]
	s_and_b64 s[4:5], s[2:3], s[6:7]
	s_and_b64 s[2:3], s[10:11], exec
	s_and_b64 s[0:1], s[4:5], exec
	s_or_b64 s[6:7], s[0:1], s[2:3]
	s_cmp_eq_u64 s[6:7], 0
	s_cbranch_scc1 .LBB0_511
	s_and_saveexec_b64 s[6:7], s[10:11]
	s_cbranch_execz .LBB0_508
	v_mov_b32_e32 v4, s3
	v_mov_b32_e32 v5, s2
	v_cndmask_b32_e32 v4, v4, v5, vcc
	v_and_b32_e32 v4, v4, v218
	v_bcnt_u32_b32 v4, v4, 0
	v_cndmask_b32_e32 v5, v187, v173, vcc
	v_add3_u32 v4, v5, v214, v4
	v_lshl_add_u32 v5, v4, 2, v190
	ds_write_b32 v5, v3
	v_lshlrev_b32_e32 v3, 1, v4
	v_sub_u32_e32 v3, v5, v3
	ds_write_b16 v3, v78 offset:10240

; DI f32x16 mfma32(bf16x8 a, bf16x8 b, f32x16 c) { return __builtin_amdgcn_mfma_f32_32x32x16_bf16(a, b, c, 0, 0, 0); }
; DI u32 mono_key(float f) { u32 u = __float_as_uint(f); return (u & 0x80000000u) ? ~u : (u | 0x80000000u); }
; DI void dsa_item(const Params& p, int l, int tile32, int b, char* smem) {
;     ...
;       for (int t = 0; t < 4; ++t) {
;         const int key = (g * 4 + t) * 32 + c31;
;         f32x16 acc;
; #pragma unroll
;         for (int j = 0; j < 16; ++j) acc[j] = 0.f;
; #pragma unroll
;         for (int s = 0; s < 4; ++s) acc = mfma32(qa[s], kc[t][s], acc);
;         f32x2 ss2 = f32x2{0.f, 0.f};
; #pragma unroll
;         for (int hq = 0; hq < 8; ++hq) {
;           const f32x2 rr = f32x2{__builtin_amdgcn_fmed3f(acc[2 * hq], 0.f, 3.0e38f), __builtin_amdgcn_fmed3f(acc[2 * hq + 1], 0.f, 3.0e38f)};
;           ss2 = __builtin_elementwise_fma(wq2[hq], rr, ss2);
;         }
;         const float s0 = ss2.x, s1 = ss2.y;
;         const u32 k0 = mono_key(s0), k1 = mono_key(s1);
;         const bool c0 = (key <= qpos0) && (k0 > tauA), c1 = (key <= qpos0 + 1) && (k1 > tauB);
;         const u64 m0 = __ballot(c0), m1 = __ballot(c1);
;         if (m0 | m1) {
;           const u32 h0 = hh ? (u32)(m0 >> 32) : (u32)m0, h1 = hh ? (u32)(m1 >> 32) : (u32)m1;
;           const int pA = (hh ? cnt2 : cnt0) + __popc(h0 & lmask), pB = (hh ? cnt3 : cnt1) + __popc(h1 & lmask);
;           if (c0) { ckey[(2 * hh) * DCAP + pA] = k0; cidx[(2 * hh) * DCAP + pA] = (u16)key; }
;           if (c1) { ckey[(2 * hh + 1) * DCAP + pB] = k1; cidx[(2 * hh + 1) * DCAP + pB] = (u16)key; }
;           cnt0 += __popc((u32)m0); cnt2 += __popc((u32)(m0 >> 32));
;           cnt1 += __popc((u32)m1); cnt3 += __popc((u32)(m1 >> 32));
;         }
.LBB0_511:
	v_mfma_f32_32x32x16_bf16 v[2:17], v[18:21], v[70:73], 0
	v_mfma_f32_32x32x16_bf16 v[2:17], v[22:25], v[66:69], v[2:17]
	v_mfma_f32_32x32x16_bf16 v[2:17], v[26:29], v[62:65], v[2:17]
	v_or_b32_e32 v62, 64, v95
	v_cmp_le_i32_e64 s[0:1], v62, v217
	v_cmp_le_i32_e64 s[2:3], v62, v219
	v_mfma_f32_32x32x16_bf16 v[2:17], v[30:33], v[58:61], v[2:17]
	s_nop 11
	v_med3_f32 v2, v2, 0, v204
	v_med3_f32 v3, v3, 0, v204
	v_med3_f32 v4, v4, 0, v204
	v_med3_f32 v5, v5, 0, v204
	v_pk_fma_f32 v[2:3], v[178:179], v[2:3], 0 op_sel_hi:[1,1,0]
	v_med3_f32 v6, v6, 0, v204
	v_med3_f32 v7, v7, 0, v204
	v_pk_fma_f32 v[2:3], v[38:39], v[4:5], v[2:3]
	v_med3_f32 v8, v8, 0, v204
	v_med3_f32 v9, v9, 0, v204
	v_pk_fma_f32 v[2:3], v[180:181], v[6:7], v[2:3]
	v_med3_f32 v10, v10, 0, v204
	v_med3_f32 v11, v11, 0, v204
	v_pk_fma_f32 v[2:3], v[40:41], v[8:9], v[2:3]
	v_med3_f32 v12, v12, 0, v204
	v_med3_f32 v13, v13, 0, v204
	v_pk_fma_f32 v[2:3], v[182:183], v[10:11], v[2:3]
	v_med3_f32 v14, v14, 0, v204
	v_med3_f32 v15, v15, 0, v204
	v_pk_fma_f32 v[2:3], v[34:35], v[12:13], v[2:3]
	v_med3_f32 v16, v16, 0, v204
	v_med3_f32 v17, v17, 0, v204
	v_pk_fma_f32 v[2:3], v[184:185], v[14:15], v[2:3]
	s_nop 0
	v_pk_fma_f32 v[4:5], v[36:37], v[16:17], v[2:3]
	s_nop 0
	v_not_b32_e32 v2, v4
	v_or_b32_e32 v3, 0x80000000, v4
	v_cmp_gt_i32_e64 s[4:5], 0, v4
	v_not_b32_e32 v6, v5
	v_or_b32_e32 v7, 0x80000000, v5
	v_cndmask_b32_e64 v3, v3, v2, s[4:5]
	v_cmp_gt_i32_e64 s[4:5], 0, v5
	s_nop 1
	v_cndmask_b32_e64 v2, v7, v6, s[4:5]
	v_cmp_gt_u32_e64 s[4:5], v3, v0
	v_cmp_gt_u32_e64 s[6:7], v2, v94
	s_and_b64 s[10:11], s[0:1], s[4:5]
	s_and_b64 s[4:5], s[2:3], s[6:7]
	s_and_b64 s[2:3], s[10:11], exec
	s_and_b64 s[0:1], s[4:5], exec
	s_or_b64 s[6:7], s[0:1], s[2:3]
	s_cmp_eq_u64 s[6:7], 0
	s_cbranch_scc1 .LBB0_517
	s_and_saveexec_b64 s[6:7], s[10:11]
	s_cbranch_execz .LBB0_514
	v_mov_b32_e32 v4, s3
	v_mov_b32_e32 v5, s2
	v_cndmask_b32_e32 v4, v4, v5, vcc
	v_and_b32_e32 v4, v4, v218
	v_bcnt_u32_b32 v4, v4, 0
	v_cndmask_b32_e32 v5, v187, v173, vcc
	v_add3_u32 v4, v5, v214, v4
	v_lshl_add_u32 v5, v4, 2, v190
	ds_write_b32 v5, v3
	v_lshlrev_b32_e32 v3, 1, v4
	v_sub_u32_e32 v3, v5, v3
	ds_write_b16 v3, v62 offset:10240

; DI f32x16 mfma32(bf16x8 a, bf16x8 b, f32x16 c) { return __builtin_amdgcn_mfma_f32_32x32x16_bf16(a, b, c, 0, 0, 0); }
; DI u32 mono_key(float f) { u32 u = __float_as_uint(f); return (u & 0x80000000u) ? ~u : (u | 0x80000000u); }
; DI void dsa_item(const Params& p, int l, int tile32, int b, char* smem) {
;     ...
;       for (int t = 0; t < 4; ++t) {
;         const int key = (g * 4 + t) * 32 + c31;
;         f32x16 acc;
; #pragma unroll
;         for (int j = 0; j < 16; ++j) acc[j] = 0.f;
; #pragma unroll
;         for (int s = 0; s < 4; ++s) acc = mfma32(qa[s], kc[t][s], acc);
;         f32x2 ss2 = f32x2{0.f, 0.f};
; #pragma unroll
;         for (int hq = 0; hq < 8; ++hq) {
;           const f32x2 rr = f32x2{__builtin_amdgcn_fmed3f(acc[2 * hq], 0.f, 3.0e38f), __builtin_amdgcn_fmed3f(acc[2 * hq + 1], 0.f, 3.0e38f)};
;           ss2 = __builtin_elementwise_fma(wq2[hq], rr, ss2);
;         }
;         const float s0 = ss2.x, s1 = ss2.y;
;         const u32 k0 = mono_key(s0), k1 = mono_key(s1);
;         const bool c0 = (key <= qpos0) && (k0 > tauA), c1 = (key <= qpos0 + 1) && (k1 > tauB);
;         const u64 m0 = __ballot(c0), m1 = __ballot(c1);
;         if (m0 | m1) {
;           const u32 h0 = hh ? (u32)(m0 >> 32) : (u32)m0, h1 = hh ? (u32)(m1 >> 32) : (u32)m1;
;           const int pA = (hh ? cnt2 : cnt0) + __popc(h0 & lmask), pB = (hh ? cnt3 : cnt1) + __popc(h1 & lmask);
;           if (c0) { ckey[(2 * hh) * DCAP + pA] = k0; cidx[(2 * hh) * DCAP + pA] = (u16)key; }
;           if (c1) { ckey[(2 * hh + 1) * DCAP + pB] = k1; cidx[(2 * hh + 1) * DCAP + pB] = (u16)key; }
;           cnt0 += __popc((u32)m0); cnt2 += __popc((u32)(m0 >> 32));
;           cnt1 += __popc((u32)m1); cnt3 += __popc((u32)(m1 >> 32));
;         }
.LBB0_517:
	v_mfma_f32_32x32x16_bf16 v[2:17], v[18:21], v[54:57], 0
	v_mfma_f32_32x32x16_bf16 v[2:17], v[22:25], v[50:53], v[2:17]
	v_mfma_f32_32x32x16_bf16 v[2:17], v[26:29], v[46:49], v[2:17]
	v_or_b32_e32 v46, 0x60, v95
	v_cmp_le_i32_e64 s[0:1], v46, v217
	v_cmp_le_i32_e64 s[2:3], v46, v219
	v_mfma_f32_32x32x16_bf16 v[2:17], v[30:33], v[42:45], v[2:17]
	s_nop 11
	v_med3_f32 v2, v2, 0, v204
	v_med3_f32 v3, v3, 0, v204
	v_med3_f32 v4, v4, 0, v204
	v_med3_f32 v5, v5, 0, v204
	v_pk_fma_f32 v[2:3], v[178:179], v[2:3], 0 op_sel_hi:[1,1,0]
	v_med3_f32 v6, v6, 0, v204
	v_med3_f32 v7, v7, 0, v204
	v_pk_fma_f32 v[2:3], v[38:39], v[4:5], v[2:3]
	v_med3_f32 v8, v8, 0, v204
	v_med3_f32 v9, v9, 0, v204
	v_pk_fma_f32 v[2:3], v[180:181], v[6:7], v[2:3]
	v_med3_f32 v10, v10, 0, v204
	v_med3_f32 v11, v11, 0, v204
	v_pk_fma_f32 v[2:3], v[40:41], v[8:9], v[2:3]
	v_med3_f32 v12, v12, 0, v204
	v_med3_f32 v13, v13, 0, v204
	v_pk_fma_f32 v[2:3], v[182:183], v[10:11], v[2:3]
	v_med3_f32 v14, v14, 0, v204
	v_med3_f32 v15, v15, 0, v204
	v_pk_fma_f32 v[2:3], v[34:35], v[12:13], v[2:3]
	v_med3_f32 v16, v16, 0, v204
	v_med3_f32 v17, v17, 0, v204
	v_pk_fma_f32 v[2:3], v[184:185], v[14:15], v[2:3]
	s_nop 0
	v_pk_fma_f32 v[4:5], v[36:37], v[16:17], v[2:3]
	s_nop 0
	v_not_b32_e32 v2, v4
	v_or_b32_e32 v3, 0x80000000, v4
	v_cmp_gt_i32_e64 s[4:5], 0, v4
	v_not_b32_e32 v6, v5
	v_or_b32_e32 v7, 0x80000000, v5
	v_cndmask_b32_e64 v3, v3, v2, s[4:5]
	v_cmp_gt_i32_e64 s[4:5], 0, v5
	s_nop 1
	v_cndmask_b32_e64 v2, v7, v6, s[4:5]
	v_cmp_gt_u32_e64 s[4:5], v3, v0
	v_cmp_gt_u32_e64 s[6:7], v2, v94
	s_and_b64 s[10:11], s[0:1], s[4:5]
	s_and_b64 s[4:5], s[2:3], s[6:7]
	s_and_b64 s[2:3], s[10:11], exec
	s_and_b64 s[0:1], s[4:5], exec
	s_or_b64 s[6:7], s[0:1], s[2:3]
	s_cmp_eq_u64 s[6:7], 0
	s_cbranch_scc1 .LBB0_374
	s_and_saveexec_b64 s[6:7], s[10:11]
	s_cbranch_execz .LBB0_520
	v_mov_b32_e32 v0, s3
	v_mov_b32_e32 v4, s2
	v_cndmask_b32_e32 v0, v0, v4, vcc
	v_and_b32_e32 v0, v0, v218
	v_bcnt_u32_b32 v0, v0, 0
	v_cndmask_b32_e32 v4, v187, v173, vcc
	v_add3_u32 v0, v4, v214, v0
	v_lshl_add_u32 v4, v0, 2, v190
	v_lshlrev_b32_e32 v0, 1, v0
	v_sub_u32_e32 v0, v4, v0
	ds_write_b32 v4, v3
	ds_write_b16 v0, v46 offset:10240
